# v44: up GEMM epilogue 1/rms table - the 16 sum-of-squares plane loads issued from the second-to-last K-step instead of the epilogue top (v41 + rstd load hoist)
# speedup vs baseline: 1.0012x; 1.0012x over previous
.Lrs_up:
	s_cmpk_lg_i32 s4, 0x700
	s_cbranch_scc1 .Lnl_4
	s_or_b32 s96, s36, s22
	s_ashr_i32 s97, s96, 31
	s_lshl_b64 s[96:97], s[96:97], 2
	s_add_u32 s96, s14, s96
	s_addc_u32 s97, s50, s97
	v_and_b32_e32 v220, 63, v193
	v_lshlrev_b32_e32 v220, 3, v220
	global_load_dwordx2 v[130:131], v220, s[96:97]
	s_add_u32 s96, s96, 0x20000
	s_addc_u32 s97, s97, 0
	global_load_dwordx2 v[132:133], v220, s[96:97]
	s_add_u32 s96, s96, 0x20000
	s_addc_u32 s97, s97, 0
	global_load_dwordx2 v[134:135], v220, s[96:97]
	s_add_u32 s96, s96, 0x20000
	s_addc_u32 s97, s97, 0
	global_load_dwordx2 v[136:137], v220, s[96:97]
	s_add_u32 s96, s96, 0x20000
	s_addc_u32 s97, s97, 0
	global_load_dwordx2 v[138:139], v220, s[96:97]
	s_add_u32 s96, s96, 0x20000
	s_addc_u32 s97, s97, 0
	global_load_dwordx2 v[140:141], v220, s[96:97]
	s_add_u32 s96, s96, 0x20000
	s_addc_u32 s97, s97, 0
	global_load_dwordx2 v[142:143], v220, s[96:97]
	s_add_u32 s96, s96, 0x20000
	s_addc_u32 s97, s97, 0
	global_load_dwordx2 v[144:145], v220, s[96:97]
	s_add_u32 s96, s96, 0x20000
	s_addc_u32 s97, s97, 0
	global_load_dwordx2 v[146:147], v220, s[96:97]
	s_add_u32 s96, s96, 0x20000
	s_addc_u32 s97, s97, 0
	global_load_dwordx2 v[148:149], v220, s[96:97]
	s_add_u32 s96, s96, 0x20000
	s_addc_u32 s97, s97, 0
	global_load_dwordx2 v[152:153], v220, s[96:97]
	s_add_u32 s96, s96, 0x20000
	s_addc_u32 s97, s97, 0
	global_load_dwordx2 v[154:155], v220, s[96:97]
	s_add_u32 s96, s96, 0x20000
	s_addc_u32 s97, s97, 0
	global_load_dwordx2 v[156:157], v220, s[96:97]
	s_add_u32 s96, s96, 0x20000
	s_addc_u32 s97, s97, 0
	global_load_dwordx2 v[158:159], v220, s[96:97]
	s_add_u32 s96, s96, 0x20000
	s_addc_u32 s97, s97, 0
	global_load_dwordx2 v[232:233], v220, s[96:97]
	s_add_u32 s96, s96, 0x20000
	s_addc_u32 s97, s97, 0
	global_load_dwordx2 v[128:129], v220, s[96:97]
	s_branch .Lnl_4
.LBB0_761:
	s_or_b32 s4, s36, s22
	s_mulk_i32 s34, 0x4800
	s_ashr_i32 s5, s4, 31
	s_add_i32 s16, s34, 0
	s_lshl_b64 s[12:13], s[4:5], 2
	s_waitcnt vmcnt(2)
	v_and_b32_e32 v150, 63, v193
	s_add_u32 s12, s14, s12
	s_addc_u32 s13, s50, s13
	v_lshlrev_b32_e32 v200, 3, v150
	v_mov_b32_e32 v151, v234
	s_nop 0
	s_nop 0
	s_mov_b32 s0, 0x80000
	s_nop 0
	s_mov_b32 s0, 0xa0000
	s_nop 0
	s_mov_b32 s0, 0xc0000
	s_nop 0
	s_mov_b32 s0, 0xe0000
	s_nop 0
	s_mov_b32 s0, 0x120000
	s_nop 0
	s_nop 0
	s_nop 0
	s_nop 0
	s_mov_b32 s0, 0x140000
	s_nop 0
	s_waitcnt vmcnt(6)
	s_mov_b32 s0, 0x160000
	s_nop 0
	s_mov_b32 s0, 0x180000
	s_nop 0
	s_waitcnt vmcnt(5)
	s_mov_b32 s0, 0x1a0000
	s_nop 0
	s_mov_b32 s0, 0x1c0000
	s_nop 0
	s_mov_b32 s0, 0x1e0000
	s_nop 0
	s_nop 0
	s_nop 0
	s_nop 0
	s_nop 0
	s_nop 0
	s_nop 0
	s_nop 0
	s_nop 0
	v_lshlrev_b32_e32 v151, 3, v151
	v_readlane_b32 s0, v255, 11
	s_and_b32 s5, s17, 0xc0
	s_lshl_b32 s5, s5, 2
	s_add_i32 s5, s5, 0
	v_mov_b32_e32 v176, v201
	v_mov_b32_e32 v177, v201
	v_mov_b32_e32 v174, v201
	v_mov_b32_e32 v175, v201
	v_mov_b32_e32 v178, v201
	v_mov_b32_e32 v179, v201
	s_add_i32 s7, s7, s6
	s_ashr_i32 s6, s7, 1
	v_readlane_b32 s12, v253, 14
	v_readlane_b32 s13, v253, 15
	v_cmp_lt_i32_e32 vcc, 30, v191
	s_waitcnt vmcnt(14)
	v_pk_add_f32 v[130:131], v[130:131], v[132:133]
	s_waitcnt vmcnt(12)
	v_pk_add_f32 v[132:133], v[134:135], v[136:137]
	s_nop 0
	v_pk_add_f32 v[130:131], v[130:131], v[132:133]
	s_waitcnt vmcnt(10)
	v_pk_add_f32 v[132:133], v[138:139], v[140:141]
	s_waitcnt vmcnt(8)
	v_pk_add_f32 v[134:135], v[142:143], v[144:145]
	s_nop 0
	v_pk_add_f32 v[132:133], v[132:133], v[134:135]
	s_waitcnt vmcnt(4)
	v_pk_add_f32 v[134:135], v[152:153], v[154:155]
	v_pk_add_f32 v[130:131], v[130:131], v[132:133]
	v_pk_add_f32 v[132:133], v[146:147], v[148:149]
	v_lshlrev_b32_e32 v152, 2, v192
	v_pk_add_f32 v[132:133], v[132:133], v[134:135]
	s_waitcnt vmcnt(2)
	v_pk_add_f32 v[134:135], v[156:157], v[158:159]
	s_waitcnt vmcnt(0)
	v_pk_add_f32 v[128:129], v[232:233], v[128:129]
	s_nop 0
	v_pk_add_f32 v[128:129], v[134:135], v[128:129]
	s_nop 0
	v_pk_add_f32 v[128:129], v[132:133], v[128:129]
	s_nop 0
	v_pk_add_f32 v[128:129], v[130:131], v[128:129]
	v_and_b32_e32 v130, 0xfffffe00, v151
	v_fmamk_f32 v128, v128, 0x3a800000, v238
	v_fmamk_f32 v129, v129, 0x3a800000, v238
	v_rsq_f32_e32 v128, v128
	v_rsq_f32_e32 v129, v129
	v_add_u32_e32 v130, s0, v130
	v_add_u32_e32 v131, v130, v200
	ds_write_b64 v131, v[128:129]
	v_lshl_add_u32 v128, v191, 4, v130
	ds_read_b128 v[128:131], v128
	s_waitcnt lgkmcnt(0)
	v_mov_b32_e32 v144, v128
	v_mov_b32_e32 v145, v128
	v_pk_mul_f32 v[112:113], v[112:113], v[128:129] op_sel_hi:[1,0]
	v_pk_mul_f32 v[114:115], v[114:115], v[128:129] op_sel_hi:[1,0]
	v_pk_mul_f32 v[64:65], v[64:65], v[128:129] op_sel_hi:[1,0]
	v_pk_mul_f32 v[66:67], v[66:67], v[128:129] op_sel_hi:[1,0]
	v_pk_mul_f32 v[96:97], v[96:97], v[128:129] op_sel:[0,1]
	v_pk_mul_f32 v[98:99], v[98:99], v[128:129] op_sel:[0,1]
	v_pk_mul_f32 v[32:33], v[32:33], v[128:129] op_sel:[0,1]
	v_pk_mul_f32 v[34:35], v[34:35], v[128:129] op_sel:[0,1]
	v_mov_b32_e32 v128, v131
	v_pk_mul_f32 v[48:49], v[48:49], v[128:129] op_sel_hi:[1,0]
	v_pk_mul_f32 v[50:51], v[50:51], v[128:129] op_sel_hi:[1,0]
	v_pk_mul_f32 v[0:1], v[0:1], v[128:129] op_sel_hi:[1,0]
	v_pk_mul_f32 v[2:3], v[2:3], v[128:129] op_sel_hi:[1,0]
	v_lshl_add_u32 v128, v192, 4, s5
	v_add_u32_e32 v151, 0x24000, v128
	ds_read_b128 v[154:157], v151
	ds_read_b128 v[132:135], v151 offset:128
	ds_read_b128 v[158:161], v151 offset:1024
	ds_read_b128 v[136:139], v151 offset:1152
	ds_read_b128 v[162:165], v151 offset:2048
	ds_read_b128 v[140:143], v151 offset:2176
	ds_read_b128 v[166:169], v151 offset:3072
	ds_read_b128 v[170:173], v151 offset:3200
	v_mov_b32_e32 v148, v129
	v_mov_b32_e32 v149, v129
	v_mov_b32_e32 v128, v201
	v_mov_b32_e32 v129, v201
	s_waitcnt lgkmcnt(1)
	v_pk_fma_f32 v[180:181], v[96:97], v[162:163], v[166:167]
	v_mov_b32_dpp v128, v48 wave_shr:1 row_mask:0xf bank_mask:0xf
	v_mov_b32_dpp v129, v49 wave_shr:1 row_mask:0xf bank_mask:0xf
	v_pk_fma_f32 v[180:181], v[112:113], v[158:159], v[180:181]
	v_pk_mul_f32 v[80:81], v[80:81], v[130:131] op_sel_hi:[1,0]
	v_pk_fma_f32 v[128:129], v[154:155], v[128:129], v[180:181]
	s_waitcnt lgkmcnt(0)
	v_pk_fma_f32 v[182:183], v[32:33], v[140:141], v[170:171]
	v_mul_f32_e32 v153, 0xbfb8aa3b, v128
	v_exp_f32_e32 v153, v153
	v_mul_f32_e32 v180, 0xbfb8aa3b, v129
	v_exp_f32_e32 v181, v180
	v_mov_b32_dpp v176, v0 wave_shr:1 row_mask:0xf bank_mask:0xf
	v_add_f32_e32 v153, 1.0, v153
	v_rcp_f32_e32 v180, v153
	v_add_f32_e32 v153, 1.0, v181
	v_rcp_f32_e32 v181, v153
	v_mov_b32_dpp v177, v1 wave_shr:1 row_mask:0xf bank_mask:0xf
	v_pk_fma_f32 v[182:183], v[64:65], v[136:137], v[182:183]
	v_pk_mul_f32 v[16:17], v[16:17], v[130:131] op_sel_hi:[1,0]
	v_pk_mul_f32 v[128:129], v[128:129], v[180:181]
	v_pk_fma_f32 v[180:181], v[80:81], v[162:163], v[166:167]
	v_pk_fma_f32 v[176:177], v[132:133], v[176:177], v[182:183]
	v_pk_fma_f32 v[180:181], v[96:97], v[158:159], v[180:181]
	v_pk_mul_f32 v[128:129], v[176:177], v[128:129]
	v_pk_fma_f32 v[180:181], v[112:113], v[154:155], v[180:181]
	v_mov_b32_dpp v174, v112 wave_shl:1 row_mask:0xf bank_mask:0xf
	v_mul_f32_e32 v153, 0xbfb8aa3b, v180
	v_exp_f32_e32 v153, v153
	v_mul_f32_e32 v182, 0xbfb8aa3b, v181
	v_exp_f32_e32 v182, v182
	v_mov_b32_dpp v175, v113 wave_shl:1 row_mask:0xf bank_mask:0xf
	v_add_f32_e32 v153, 1.0, v153
	v_rcp_f32_e32 v176, v153
	v_add_f32_e32 v153, 1.0, v182
	v_rcp_f32_e32 v177, v153
	v_pk_fma_f32 v[182:183], v[16:17], v[140:141], v[170:171]
	v_mov_b32_dpp v178, v64 wave_shl:1 row_mask:0xf bank_mask:0xf
	v_pk_fma_f32 v[182:183], v[32:33], v[136:137], v[182:183]
	v_pk_mul_f32 v[176:177], v[180:181], v[176:177]
	v_pk_fma_f32 v[180:181], v[48:49], v[162:163], v[166:167]
	v_pk_fma_f32 v[162:163], v[162:163], v[174:175], v[166:167]
	v_pk_fma_f32 v[180:181], v[80:81], v[158:159], v[180:181]
	v_pk_fma_f32 v[182:183], v[64:65], v[132:133], v[182:183]
	v_pk_fma_f32 v[180:181], v[96:97], v[154:155], v[180:181]
	v_pk_fma_f32 v[158:159], v[48:49], v[158:159], v[162:163]
	v_mul_f32_e32 v153, 0xbfb8aa3b, v180
	v_exp_f32_e32 v153, v153
	v_mul_f32_e32 v184, 0xbfb8aa3b, v181
	v_exp_f32_e32 v184, v184
	v_pk_mul_f32 v[176:177], v[182:183], v[176:177]
	v_add_f32_e32 v153, 1.0, v153
	v_rcp_f32_e32 v182, v153
	v_add_f32_e32 v153, 1.0, v184
	v_pk_fma_f32 v[154:155], v[80:81], v[154:155], v[158:159]
	v_rcp_f32_e32 v183, v153
	v_mul_f32_e32 v153, 0xbfb8aa3b, v154
	v_exp_f32_e32 v153, v153
	v_mul_f32_e32 v158, 0xbfb8aa3b, v155
	v_exp_f32_e32 v163, v158
	v_mov_b32_dpp v179, v65 wave_shl:1 row_mask:0xf bank_mask:0xf
	v_add_f32_e32 v153, 1.0, v153
	v_rcp_f32_e32 v162, v153
	v_add_f32_e32 v153, 1.0, v163
	v_rcp_f32_e32 v163, v153
	v_pk_fma_f32 v[184:185], v[0:1], v[140:141], v[170:171]
	v_pk_fma_f32 v[140:141], v[140:141], v[178:179], v[170:171]
	v_pk_fma_f32 v[184:185], v[16:17], v[136:137], v[184:185]
	v_pk_fma_f32 v[136:137], v[0:1], v[136:137], v[140:141]
	v_pk_fma_f32 v[184:185], v[32:33], v[132:133], v[184:185]
	v_pk_fma_f32 v[132:133], v[16:17], v[132:133], v[136:137]
	v_pk_mul_f32 v[136:137], v[154:155], v[162:163]
	v_pk_fma_f32 v[166:167], v[98:99], v[164:165], v[168:169]
	v_pk_mul_f32 v[136:137], v[132:133], v[136:137]
	v_mov_b32_e32 v132, v201
	v_mov_b32_e32 v133, v201
	v_pk_fma_f32 v[166:167], v[114:115], v[160:161], v[166:167]
	v_mov_b32_dpp v132, v50 wave_shr:1 row_mask:0xf bank_mask:0xf
	v_mov_b32_dpp v133, v51 wave_shr:1 row_mask:0xf bank_mask:0xf
	v_pk_fma_f32 v[132:133], v[156:157], v[132:133], v[166:167]
	v_pk_mul_f32 v[82:83], v[82:83], v[130:131] op_sel_hi:[1,0]
	v_mul_f32_e32 v153, 0xbfb8aa3b, v132
	v_exp_f32_e32 v153, v153
	v_mul_f32_e32 v166, 0xbfb8aa3b, v133
	v_exp_f32_e32 v167, v166
	v_mov_b32_e32 v154, v201
	v_add_f32_e32 v153, 1.0, v153
	v_rcp_f32_e32 v166, v153
	v_add_f32_e32 v153, 1.0, v167
	v_rcp_f32_e32 v167, v153
	v_mov_b32_e32 v155, v201
	v_pk_fma_f32 v[170:171], v[34:35], v[142:143], v[172:173]
	v_mov_b32_dpp v154, v2 wave_shr:1 row_mask:0xf bank_mask:0xf
	v_pk_mul_f32 v[132:133], v[132:133], v[166:167]
	v_pk_fma_f32 v[166:167], v[82:83], v[164:165], v[168:169]
	v_mov_b32_dpp v155, v3 wave_shr:1 row_mask:0xf bank_mask:0xf
	v_pk_fma_f32 v[166:167], v[98:99], v[160:161], v[166:167]
	v_pk_fma_f32 v[170:171], v[66:67], v[138:139], v[170:171]
	v_pk_fma_f32 v[166:167], v[114:115], v[156:157], v[166:167]
	v_pk_fma_f32 v[154:155], v[134:135], v[154:155], v[170:171]
	v_mul_f32_e32 v153, 0xbfb8aa3b, v166
	v_mul_f32_e32 v170, 0xbfb8aa3b, v167
	v_exp_f32_e32 v153, v153
	v_exp_f32_e32 v170, v170
	v_pk_mul_f32 v[154:155], v[154:155], v[132:133]
	v_pk_mul_f32 v[18:19], v[18:19], v[130:131] op_sel_hi:[1,0]
	v_add_f32_e32 v132, 1.0, v153
	v_add_f32_e32 v133, 1.0, v170
	v_rcp_f32_e32 v132, v132
	v_rcp_f32_e32 v133, v133
	v_mov_b32_e32 v140, v201
	v_mov_b32_e32 v141, v201
	v_pk_fma_f32 v[170:171], v[18:19], v[142:143], v[172:173]
	v_pk_mul_f32 v[132:133], v[166:167], v[132:133]
	v_pk_fma_f32 v[166:167], v[50:51], v[164:165], v[168:169]
	v_mov_b32_dpp v140, v114 wave_shl:1 row_mask:0xf bank_mask:0xf
	v_pk_fma_f32 v[166:167], v[82:83], v[160:161], v[166:167]
	v_mov_b32_dpp v141, v115 wave_shl:1 row_mask:0xf bank_mask:0xf
	v_pk_fma_f32 v[166:167], v[98:99], v[156:157], v[166:167]
	v_pk_fma_f32 v[170:171], v[34:35], v[138:139], v[170:171]
	v_mul_f32_e32 v153, 0xbfb8aa3b, v166
	v_mul_f32_e32 v174, 0xbfb8aa3b, v167
	v_exp_f32_e32 v153, v153
	v_exp_f32_e32 v174, v174
	v_pk_fma_f32 v[140:141], v[164:165], v[140:141], v[168:169]
	v_pk_fma_f32 v[170:171], v[66:67], v[134:135], v[170:171]
	v_pk_fma_f32 v[140:141], v[50:51], v[160:161], v[140:141]
	v_pk_mul_f32 v[170:171], v[170:171], v[132:133]
	v_add_f32_e32 v132, 1.0, v153
	v_add_f32_e32 v133, 1.0, v174
	v_pk_fma_f32 v[140:141], v[82:83], v[156:157], v[140:141]
	v_rcp_f32_e32 v132, v132
	v_rcp_f32_e32 v133, v133
	v_mul_f32_e32 v153, 0xbfb8aa3b, v140
	v_mul_f32_e32 v156, 0xbfb8aa3b, v141
	v_exp_f32_e32 v153, v153
	v_exp_f32_e32 v160, v156
	v_pk_fma_f32 v[174:175], v[2:3], v[142:143], v[172:173]
	v_pk_mul_f32 v[132:133], v[166:167], v[132:133]
	v_pk_fma_f32 v[174:175], v[18:19], v[138:139], v[174:175]
	v_mov_b32_e32 v162, v201
	v_pk_fma_f32 v[174:175], v[34:35], v[134:135], v[174:175]
	v_mov_b32_e32 v163, v201
	v_pk_mul_f32 v[156:157], v[174:175], v[132:133]
	v_add_f32_e32 v132, 1.0, v153
	v_add_f32_e32 v133, 1.0, v160
	v_rcp_f32_e32 v132, v132
	v_rcp_f32_e32 v133, v133
	v_mov_b32_dpp v162, v66 wave_shl:1 row_mask:0xf bank_mask:0xf
	v_mov_b32_dpp v163, v67 wave_shl:1 row_mask:0xf bank_mask:0xf
	v_pk_fma_f32 v[142:143], v[142:143], v[162:163], v[172:173]
	v_pk_mul_f32 v[132:133], v[140:141], v[132:133]
	v_pk_fma_f32 v[138:139], v[2:3], v[138:139], v[142:143]
	v_pk_mul_f32 v[180:181], v[180:181], v[182:183]
	v_pk_fma_f32 v[134:135], v[18:19], v[134:135], v[138:139]
	s_ashr_i32 s5, s4, 7
	v_pk_mul_f32 v[134:135], v[134:135], v[132:133]
	v_lshlrev_b32_e32 v133, 3, v192
	v_mul_u32_u24_e32 v132, 0x140, v191
	v_pk_mul_f32 v[158:159], v[184:185], v[180:181]
	v_add3_u32 v133, s16, v133, v132
	v_cvt_pk_bf16_f32 v128, v128, v129
	v_cvt_pk_bf16_f32 v129, v154, v155
	v_cvt_pk_bf16_f32 v138, v176, v177
	v_cvt_pk_bf16_f32 v139, v170, v171
	s_mul_hi_i32 s7, s5, 0x16000
	s_mul_i32 s5, s5, 0x16000
	ds_write2_b64 v133, v[128:129], v[138:139] offset1:10
	v_cvt_pk_bf16_f32 v128, v158, v159
	v_cvt_pk_bf16_f32 v129, v156, v157
	v_cvt_pk_bf16_f32 v136, v136, v137
	v_cvt_pk_bf16_f32 v137, v134, v135
	s_add_u32 s34, s12, s5
	ds_write2_b64 v133, v[128:129], v[136:137] offset0:20 offset1:30
	v_mov_b32_e32 v146, v130
	v_mov_b32_e32 v147, v130
	v_mov_b32_e32 v130, v131
	s_addc_u32 s35, s13, s7
	v_or_b32_e32 v128, s6, v152
	s_and_saveexec_b64 s[12:13], vcc
	s_xor_b64 s[42:43], exec, s[12:13]
	s_cbranch_execz .LBB0_763
	v_ashrrev_i32_e32 v129, 31, v128
	v_lshl_add_u64 v[32:33], v[128:129], 2, s[34:35]
	v_add_co_u32_e32 v34, vcc, 0xb000, v32
	s_nop 1
	v_addc_co_u32_e32 v35, vcc, 0, v33, vcc
	global_store_dwordx4 v[34:35], v[80:83], off
	v_add_co_u32_e32 v34, vcc, 0x10000, v32
	s_nop 1
	v_addc_co_u32_e32 v35, vcc, 0, v33, vcc
	global_store_dwordx4 v[34:35], v[48:51], off offset:2048
	v_add_co_u32_e32 v34, vcc, 0xd000, v32
	s_nop 1
	v_addc_co_u32_e32 v35, vcc, 0, v33, vcc
	global_store_dwordx4 v[34:35], v[16:19], off offset:3072
	s_nop 1
	v_add_co_u32_e32 v16, vcc, 0x13000, v32
	s_nop 1
	v_addc_co_u32_e32 v17, vcc, 0, v33, vcc
	global_store_dwordx4 v[16:17], v[0:3], off offset:1024
